# GEMM: m0 writes moved out of MFMA segment tails; dead per-row epilogue precomputations removed
# baseline (speedup 1.0000x reference)
; #define PG8_STAGE(bufoff, gbase, voff) do { _Pragma("unroll") for (int _i = 0; _i < 2; ++_i) \
;         __builtin_amdgcn_global_load_lds((const unsigned*)((const char*)(gbase) + (voff)[_i]), (LAS unsigned*)(lds + (bufoff) + ldsw + _i * 8192), 16, 0, 0); } while (0)
; #define PG8_LDA(dst, b, h) do { _Pragma("unroll") for (int m = 0; m < 4; ++m) _Pragma("unroll") for (int k = 0; k < 2; ++k) dst[m][k] = *(const LAS bf16x8*)(lds + PG8_SA(b, h) + aoff + m * 2048 + k * 1024); } while (0)
; #define PG8_WAIT_V(n) asm volatile("s_waitcnt vmcnt(" #n ")" ::: "memory")
; #define PG8_WAIT_L(n) asm volatile("s_waitcnt lgkmcnt(" #n ")" ::: "memory")
; template <class Epi>
; DI void gemm_phase(LAS unsigned char* lds, const Gemm g, const StaticOrder& S, const Epi& E, const int tid) {
;     ...
;         for (int t = 0; t < nt; t += 2) {
;             const bool last = (t == nt - 2);
;             const char* a1 = cA + (size_t)(t + 1) * kstep;
;             const char* a2 = last ? nA : cA + (size_t)(t + 2) * kstep; const char* b2 = last ? nB : cB + (size_t)(t + 2) * kstep;
;             const char* a3 = a2 + kstep; const char* b3 = b2 + kstep;
;             PG8_LDB(B0, 0, 0); PG8_SCHED; PG8_LDA(At, 0, 0); PG8_STAGE(PG8_SA(1, 1), a1 + hstep, voffA);
;             PG8_WAIT_L(8); PG8_BAR; PG8_WAIT_L(0); PG8_MMA(0, 0, At, B0); PG8_BAR; PG8_SCHED;
;             PG8_LDB(B1, 0, 1); PG8_STAGE(PG8_SB(0, 0), b2, voffB);
;             PG8_BAR; PG8_WAIT_L(0); PG8_MMA(0, 1, At, B1); PG8_BAR;
;             PG8_LDA(At, 0, 1); PG8_STAGE(PG8_SA(0, 0), a2, voffA);
;             PG8_BAR; PG8_WAIT_L(0); PG8_MMA(1, 0, At, B0); PG8_BAR; PG8_SCHED;
;             PG8_STAGE(PG8_SB(0, 1), b2 + hstep, voffB);
;             PG8_WAIT_V(6); PG8_BAR; PG8_MMA(1, 1, At, B1); PG8_BAR;
;             PG8_LDB(B0, 1, 0); PG8_SCHED; PG8_LDA(At, 1, 0); PG8_STAGE(PG8_SA(0, 1), a2 + hstep, voffA);
;             PG8_WAIT_L(8); PG8_BAR; PG8_WAIT_L(0); PG8_MMA(0, 0, At, B0); PG8_BAR; PG8_SCHED;
;             PG8_LDB(B1, 1, 1); PG8_STAGE(PG8_SB(1, 0), b3, voffB);
;             PG8_BAR; PG8_WAIT_L(0); PG8_MMA(0, 1, At, B1); PG8_BAR;
;             PG8_LDA(At, 1, 1); PG8_STAGE(PG8_SA(1, 0), a3, voffA);
;             PG8_BAR; PG8_WAIT_L(0); PG8_MMA(1, 0, At, B0); PG8_BAR; PG8_SCHED;
;             PG8_STAGE(PG8_SB(1, 1), b3 + hstep, voffB);
;             PG8_WAIT_V(6); PG8_BAR; PG8_MMA(1, 1, At, B1); PG8_BAR;
.LBB0_742:
	s_add_u32 s20, s20, 0x80
	s_addc_u32 s21, s21, 0
	s_add_u32 s81, s18, 0x100
	s_addc_u32 s82, s19, 0
	s_mov_b32 s18, 0
	ds_read_b128 v[138:141], v212
	ds_read_b128 v[150:153], v212 offset:1024
	ds_read_b128 v[154:157], v212 offset:2048
	ds_read_b128 v[158:161], v212 offset:3072
	s_add_i32 s83, s18, 2
	s_add_u32 s22, s20, 0x80
	s_addc_u32 s19, s21, 0
	s_cmp_eq_u32 s60, s18
	s_cselect_b32 s18, s8, s22
	s_cselect_b32 s19, s9, s19
	s_cselect_b32 s23, s17, s82
	s_cselect_b32 s22, s16, s81
	s_add_i32 m0, s49, 0xc000
	ds_read_b128 v[162:165], v148
	ds_read_b128 v[166:169], v148 offset:1024
	ds_read_b128 v[170:173], v148 offset:2048
	ds_read_b128 v[174:177], v148 offset:3072
	ds_read_b128 v[178:181], v148 offset:4096
	ds_read_b128 v[182:185], v148 offset:5120
	ds_read_b128 v[186:189], v148 offset:6144
	ds_read_b128 v[190:193], v148 offset:7168
	global_load_lds_dwordx4 v134, s[20:21]
	s_add_i32 m0, s49, 0xe000
	s_nop 0
	global_load_lds_dwordx4 v136, s[20:21]
	s_waitcnt lgkmcnt(8)
	s_barrier
	s_waitcnt lgkmcnt(0)
	s_setprio 1
	v_mfma_f32_16x16x32_bf16 v[24:27], v[138:141], v[162:165], 0
	v_mfma_f32_16x16x32_bf16 v[28:31], v[154:157], v[162:165], 0
	v_mfma_f32_16x16x32_bf16 v[16:19], v[138:141], v[170:173], 0
	v_mfma_f32_16x16x32_bf16 v[20:23], v[154:157], v[170:173], 0
	v_mfma_f32_16x16x32_bf16 v[8:11], v[138:141], v[178:181], 0
	v_mfma_f32_16x16x32_bf16 v[12:15], v[154:157], v[178:181], 0
	v_mfma_f32_16x16x32_bf16 v[0:3], v[138:141], v[186:189], 0
	v_mfma_f32_16x16x32_bf16 v[4:7], v[154:157], v[186:189], 0
	v_mfma_f32_16x16x32_bf16 v[24:27], v[150:153], v[166:169], v[24:27]
	v_mfma_f32_16x16x32_bf16 v[28:31], v[158:161], v[166:169], v[28:31]
	v_mfma_f32_16x16x32_bf16 v[16:19], v[150:153], v[174:177], v[16:19]
	v_mfma_f32_16x16x32_bf16 v[20:23], v[158:161], v[174:177], v[20:23]
	v_mfma_f32_16x16x32_bf16 v[8:11], v[150:153], v[182:185], v[8:11]
	v_mfma_f32_16x16x32_bf16 v[12:15], v[158:161], v[182:185], v[12:15]
	v_mfma_f32_16x16x32_bf16 v[0:3], v[150:153], v[190:193], v[0:3]
	v_mfma_f32_16x16x32_bf16 v[4:7], v[158:161], v[190:193], v[4:7]
	s_setprio 0
	s_barrier
	s_add_i32 s89, 0, 0x14000
	s_add_i32 vcc_lo, s26, s4
	s_mov_b32 m0, vcc_lo
	ds_read_b128 v[194:197], v213
	ds_read_b128 v[200:203], v213 offset:1024
	ds_read_b128 v[204:207], v213 offset:2048
	ds_read_b128 v[208:211], v213 offset:3072
	global_load_lds_dwordx4 v198, s[22:23]
	s_add_i32 m0, vcc_lo, 0x2000
	s_nop 0
	global_load_lds_dwordx4 v128, s[22:23]
	s_barrier
	s_waitcnt lgkmcnt(0)
	s_setprio 1
	v_mfma_f32_16x16x32_bf16 v[88:91], v[194:197], v[162:165], 0
	v_mfma_f32_16x16x32_bf16 v[96:99], v[204:207], v[162:165], 0
	v_mfma_f32_16x16x32_bf16 v[80:83], v[194:197], v[170:173], 0
	v_mfma_f32_16x16x32_bf16 v[84:87], v[204:207], v[170:173], 0
	v_mfma_f32_16x16x32_bf16 v[72:75], v[194:197], v[178:181], 0
	v_mfma_f32_16x16x32_bf16 v[76:79], v[204:207], v[178:181], 0
	v_mfma_f32_16x16x32_bf16 v[56:59], v[194:197], v[186:189], 0
	v_mfma_f32_16x16x32_bf16 v[64:67], v[204:207], v[186:189], 0
	v_mfma_f32_16x16x32_bf16 v[88:91], v[200:203], v[166:169], v[88:91]
	v_mfma_f32_16x16x32_bf16 v[96:99], v[208:211], v[166:169], v[96:99]
	v_mfma_f32_16x16x32_bf16 v[80:83], v[200:203], v[174:177], v[80:83]
	v_mfma_f32_16x16x32_bf16 v[84:87], v[208:211], v[174:177], v[84:87]
	v_mfma_f32_16x16x32_bf16 v[72:75], v[200:203], v[182:185], v[72:75]
	v_mfma_f32_16x16x32_bf16 v[76:79], v[208:211], v[182:185], v[76:79]
	v_mfma_f32_16x16x32_bf16 v[56:59], v[200:203], v[190:193], v[56:59]
	v_mfma_f32_16x16x32_bf16 v[64:67], v[208:211], v[190:193], v[64:67]
	s_setprio 0
	s_barrier
	s_mov_b32 m0, s49
	ds_read_b128 v[162:165], v148 offset:16384
	ds_read_b128 v[166:169], v148 offset:17408
	ds_read_b128 v[170:173], v148 offset:18432
	ds_read_b128 v[174:177], v148 offset:19456
	ds_read_b128 v[178:181], v148 offset:20480
	ds_read_b128 v[182:185], v148 offset:21504
	ds_read_b128 v[186:189], v148 offset:22528
	ds_read_b128 v[190:193], v148 offset:23552
	global_load_lds_dwordx4 v132, s[18:19]
	s_mov_b32 m0, s52
	s_nop 0
	global_load_lds_dwordx4 v130, s[18:19]
	s_barrier
	s_waitcnt lgkmcnt(0)
	s_setprio 1
	v_mfma_f32_16x16x32_bf16 v[60:63], v[138:141], v[162:165], 0
	v_mfma_f32_16x16x32_bf16 v[68:71], v[154:157], v[162:165], 0
	v_mfma_f32_16x16x32_bf16 v[48:51], v[138:141], v[170:173], 0
	v_mfma_f32_16x16x32_bf16 v[52:55], v[154:157], v[170:173], 0
	v_mfma_f32_16x16x32_bf16 v[40:43], v[138:141], v[178:181], 0
	v_mfma_f32_16x16x32_bf16 v[44:47], v[154:157], v[178:181], 0
	v_mfma_f32_16x16x32_bf16 v[32:35], v[138:141], v[186:189], 0
	v_mfma_f32_16x16x32_bf16 v[36:39], v[154:157], v[186:189], 0
	v_mfma_f32_16x16x32_bf16 v[60:63], v[150:153], v[166:169], v[60:63]
	v_mfma_f32_16x16x32_bf16 v[68:71], v[158:161], v[166:169], v[68:71]
	v_mfma_f32_16x16x32_bf16 v[48:51], v[150:153], v[174:177], v[48:51]
	v_mfma_f32_16x16x32_bf16 v[52:55], v[158:161], v[174:177], v[52:55]
	v_mfma_f32_16x16x32_bf16 v[40:43], v[150:153], v[182:185], v[40:43]
	v_mfma_f32_16x16x32_bf16 v[44:47], v[158:161], v[182:185], v[44:47]
	v_mfma_f32_16x16x32_bf16 v[32:35], v[150:153], v[190:193], v[32:35]
	v_mfma_f32_16x16x32_bf16 v[36:39], v[158:161], v[190:193], v[36:39]
	s_setprio 0
	s_barrier
	s_add_u32 s22, s22, s84
	s_addc_u32 s23, s23, 0
	s_add_i32 s89, s89, s4
	s_mov_b32 m0, s89
	s_nop 0
	global_load_lds_dwordx4 v198, s[22:23]
	s_add_i32 m0, s89, 0x2000
	s_nop 0
	global_load_lds_dwordx4 v128, s[22:23]
	s_add_i32 s22, 0, 0x18000
	s_waitcnt vmcnt(6)
	s_barrier
; #define PG8_STAGE(bufoff, gbase, voff) do { _Pragma("unroll") for (int _i = 0; _i < 2; ++_i) \
;         __builtin_amdgcn_global_load_lds((const unsigned*)((const char*)(gbase) + (voff)[_i]), (LAS unsigned*)(lds + (bufoff) + ldsw + _i * 8192), 16, 0, 0); } while (0)
; #define PG8_LDA(dst, b, h) do { _Pragma("unroll") for (int m = 0; m < 4; ++m) _Pragma("unroll") for (int k = 0; k < 2; ++k) dst[m][k] = *(const LAS bf16x8*)(lds + PG8_SA(b, h) + aoff + m * 2048 + k * 1024); } while (0)
; #define PG8_LDB(dst, b, h) do { _Pragma("unroll") for (int n = 0; n < 2; ++n) _Pragma("unroll") for (int k = 0; k < 2; ++k) dst[n][k] = *(const LAS bf16x8*)(lds + PG8_SB(b, h) + boff + n * 2048 + k * 1024); } while (0)
; #define PG8_MMA(ai, bj, At, Bt) do { __builtin_amdgcn_s_setprio(1); _Pragma("unroll") for (int m = 0; m < 4; ++m) _Pragma("unroll") for (int n = 0; n < 2; ++n) _Pragma("unroll") for (int k = 0; k < 2; ++k) \
;         acc[ai][bj][m][n] = __builtin_amdgcn_mfma_f32_16x16x32_bf16(Bt[n][k], At[m][k], acc[ai][bj][m][n], 0, 0, 0); __builtin_amdgcn_s_setprio(0); } while (0)
; #define PG8_WAIT_V(n) asm volatile("s_waitcnt vmcnt(" #n ")" ::: "memory")
; #define PG8_WAIT_L(n) asm volatile("s_waitcnt lgkmcnt(" #n ")" ::: "memory")
; #define PG8_BAR __builtin_amdgcn_s_barrier()
; #define PG8_SCHED __builtin_amdgcn_sched_barrier(0)
; template <class Epi>
; DI void gemm_phase(LAS unsigned char* lds, const Gemm g, const StaticOrder& S, const Epi& E, const int tid) {
;     ...
;             PG8_WAIT_V(6); PG8_BAR; PG8_MMA(1, 1, At, B1); PG8_BAR;
;             PG8_LDB(B0, 1, 0); PG8_SCHED; PG8_LDA(At, 1, 0); PG8_STAGE(PG8_SA(0, 1), a2 + hstep, voffA);
;             PG8_WAIT_L(8); PG8_BAR; PG8_WAIT_L(0); PG8_MMA(0, 0, At, B0); PG8_BAR; PG8_SCHED;
;             PG8_LDB(B1, 1, 1); PG8_STAGE(PG8_SB(1, 0), b3, voffB);
;             PG8_BAR; PG8_WAIT_L(0); PG8_MMA(0, 1, At, B1); PG8_BAR;
;             PG8_LDA(At, 1, 1); PG8_STAGE(PG8_SA(1, 0), a3, voffA);
	s_setprio 1
	v_mfma_f32_16x16x32_bf16 v[120:123], v[194:197], v[162:165], 0
	v_mfma_f32_16x16x32_bf16 v[124:127], v[204:207], v[162:165], 0
	v_mfma_f32_16x16x32_bf16 v[112:115], v[194:197], v[170:173], 0
	v_mfma_f32_16x16x32_bf16 v[116:119], v[204:207], v[170:173], 0
	v_mfma_f32_16x16x32_bf16 v[104:107], v[194:197], v[178:181], 0
	v_mfma_f32_16x16x32_bf16 v[108:111], v[204:207], v[178:181], 0
	v_mfma_f32_16x16x32_bf16 v[92:95], v[194:197], v[186:189], 0
	v_mfma_f32_16x16x32_bf16 v[100:103], v[204:207], v[186:189], 0
	v_mfma_f32_16x16x32_bf16 v[120:123], v[200:203], v[166:169], v[120:123]
	v_mfma_f32_16x16x32_bf16 v[124:127], v[208:211], v[166:169], v[124:127]
	v_mfma_f32_16x16x32_bf16 v[112:115], v[200:203], v[174:177], v[112:115]
	v_mfma_f32_16x16x32_bf16 v[116:119], v[208:211], v[174:177], v[116:119]
	v_mfma_f32_16x16x32_bf16 v[104:107], v[200:203], v[182:185], v[104:107]
	v_mfma_f32_16x16x32_bf16 v[108:111], v[208:211], v[182:185], v[108:111]
	v_mfma_f32_16x16x32_bf16 v[92:95], v[200:203], v[190:193], v[92:95]
	v_mfma_f32_16x16x32_bf16 v[100:103], v[208:211], v[190:193], v[100:103]
	s_setprio 0
	s_barrier
	ds_read_b128 v[138:141], v214
	ds_read_b128 v[150:153], v214 offset:1024
	ds_read_b128 v[154:157], v214 offset:2048
	ds_read_b128 v[158:161], v214 offset:3072
	s_add_u32 s18, s18, s84
	s_addc_u32 s19, s19, 0
	s_mov_b32 m0, s53
	ds_read_b128 v[162:165], v148 offset:32768
	ds_read_b128 v[166:169], v148 offset:33792
	ds_read_b128 v[170:173], v148 offset:34816
	ds_read_b128 v[174:177], v148 offset:35840
	ds_read_b128 v[178:181], v148 offset:36864
	ds_read_b128 v[182:185], v148 offset:37888
	ds_read_b128 v[186:189], v148 offset:38912
	ds_read_b128 v[190:193], v148 offset:39936
	global_load_lds_dwordx4 v132, s[18:19]
	s_mov_b32 m0, s54
	s_nop 0
	global_load_lds_dwordx4 v130, s[18:19]
	s_waitcnt lgkmcnt(8)
	s_barrier
	s_waitcnt lgkmcnt(0)
	s_setprio 1
	v_mfma_f32_16x16x32_bf16 v[24:27], v[138:141], v[162:165], v[24:27]
	v_mfma_f32_16x16x32_bf16 v[28:31], v[154:157], v[162:165], v[28:31]
	v_mfma_f32_16x16x32_bf16 v[16:19], v[138:141], v[170:173], v[16:19]
	v_mfma_f32_16x16x32_bf16 v[20:23], v[154:157], v[170:173], v[20:23]
	v_mfma_f32_16x16x32_bf16 v[8:11], v[138:141], v[178:181], v[8:11]
	v_mfma_f32_16x16x32_bf16 v[12:15], v[154:157], v[178:181], v[12:15]
	v_mfma_f32_16x16x32_bf16 v[0:3], v[138:141], v[186:189], v[0:3]
	v_mfma_f32_16x16x32_bf16 v[4:7], v[154:157], v[186:189], v[4:7]
	v_mfma_f32_16x16x32_bf16 v[24:27], v[150:153], v[166:169], v[24:27]
	v_mfma_f32_16x16x32_bf16 v[28:31], v[158:161], v[166:169], v[28:31]
	v_mfma_f32_16x16x32_bf16 v[16:19], v[150:153], v[174:177], v[16:19]
	v_mfma_f32_16x16x32_bf16 v[20:23], v[158:161], v[174:177], v[20:23]
	v_mfma_f32_16x16x32_bf16 v[8:11], v[150:153], v[182:185], v[8:11]
	v_mfma_f32_16x16x32_bf16 v[12:15], v[158:161], v[182:185], v[12:15]
	v_mfma_f32_16x16x32_bf16 v[0:3], v[150:153], v[190:193], v[0:3]
	v_mfma_f32_16x16x32_bf16 v[4:7], v[158:161], v[190:193], v[4:7]
	s_setprio 0
	s_barrier
	s_add_i32 s18, 0, 0x1c000
	s_add_i32 s19, s22, s4
	s_mov_b32 m0, s19
	ds_read_b128 v[194:197], v215
	ds_read_b128 v[200:203], v215 offset:1024
	ds_read_b128 v[204:207], v215 offset:2048
	ds_read_b128 v[208:211], v215 offset:3072
	s_add_i32 vcc_hi, s60, 2
	s_cmp_eq_u32 vcc_hi, s83
	s_cselect_b32 s100, s16, s81
	s_cselect_b32 s101, s17, s82
	s_add_u32 s100, s100, 0x80
	s_addc_u32 s101, s101, 0
	global_load_lds_dwordx4 v198, s[100:101]
	s_add_i32 m0, s19, 0x2000
	s_nop 0
	global_load_lds_dwordx4 v128, s[100:101]
	s_barrier
	s_waitcnt lgkmcnt(0)
	s_setprio 1
	v_mfma_f32_16x16x32_bf16 v[88:91], v[194:197], v[162:165], v[88:91]
	v_mfma_f32_16x16x32_bf16 v[96:99], v[204:207], v[162:165], v[96:99]
	v_mfma_f32_16x16x32_bf16 v[80:83], v[194:197], v[170:173], v[80:83]
	v_mfma_f32_16x16x32_bf16 v[84:87], v[204:207], v[170:173], v[84:87]
	v_mfma_f32_16x16x32_bf16 v[72:75], v[194:197], v[178:181], v[72:75]
	v_mfma_f32_16x16x32_bf16 v[76:79], v[204:207], v[178:181], v[76:79]
	v_mfma_f32_16x16x32_bf16 v[56:59], v[194:197], v[186:189], v[56:59]
	v_mfma_f32_16x16x32_bf16 v[64:67], v[204:207], v[186:189], v[64:67]
	v_mfma_f32_16x16x32_bf16 v[88:91], v[200:203], v[166:169], v[88:91]
	v_mfma_f32_16x16x32_bf16 v[96:99], v[208:211], v[166:169], v[96:99]
	v_mfma_f32_16x16x32_bf16 v[80:83], v[200:203], v[174:177], v[80:83]
	v_mfma_f32_16x16x32_bf16 v[84:87], v[208:211], v[174:177], v[84:87]
	v_mfma_f32_16x16x32_bf16 v[72:75], v[200:203], v[182:185], v[72:75]
	v_mfma_f32_16x16x32_bf16 v[76:79], v[208:211], v[182:185], v[76:79]
	v_mfma_f32_16x16x32_bf16 v[56:59], v[200:203], v[190:193], v[56:59]
	v_mfma_f32_16x16x32_bf16 v[64:67], v[208:211], v[190:193], v[64:67]
	s_setprio 0
	s_barrier
	s_mov_b32 m0, s55
	ds_read_b128 v[162:165], v148 offset:49152
	ds_read_b128 v[166:169], v148 offset:50176
	ds_read_b128 v[170:173], v148 offset:51200
	ds_read_b128 v[174:177], v148 offset:52224
	ds_read_b128 v[178:181], v148 offset:53248
	ds_read_b128 v[182:185], v148 offset:54272
	ds_read_b128 v[186:189], v148 offset:55296
	ds_read_b128 v[190:193], v148 offset:56320
	s_add_u32 s100, s20, 0x80
	s_addc_u32 s101, s21, 0
	s_add_i32 vcc_hi, s60, 2
	s_cmp_eq_u32 vcc_hi, s83
	s_cselect_b32 s100, s8, s100
	s_cselect_b32 s101, s9, s101
	s_add_u32 s100, s100, 0x80
	s_addc_u32 s101, s101, 0
	global_load_lds_dwordx4 v132, s[100:101]
	s_mov_b32 m0, s56
	s_nop 0
	global_load_lds_dwordx4 v130, s[100:101]
	s_barrier
; #define PG8_STAGE(bufoff, gbase, voff) do { _Pragma("unroll") for (int _i = 0; _i < 2; ++_i) \
;         __builtin_amdgcn_global_load_lds((const unsigned*)((const char*)(gbase) + (voff)[_i]), (LAS unsigned*)(lds + (bufoff) + ldsw + _i * 8192), 16, 0, 0); } while (0)
; #define PG8_LDA(dst, b, h) do { _Pragma("unroll") for (int m = 0; m < 4; ++m) _Pragma("unroll") for (int k = 0; k < 2; ++k) dst[m][k] = *(const LAS bf16x8*)(lds + PG8_SA(b, h) + aoff + m * 2048 + k * 1024); } while (0)
; #define PG8_LDB(dst, b, h) do { _Pragma("unroll") for (int n = 0; n < 2; ++n) _Pragma("unroll") for (int k = 0; k < 2; ++k) dst[n][k] = *(const LAS bf16x8*)(lds + PG8_SB(b, h) + boff + n * 2048 + k * 1024); } while (0)
; #define PG8_MMA(ai, bj, At, Bt) do { __builtin_amdgcn_s_setprio(1); _Pragma("unroll") for (int m = 0; m < 4; ++m) _Pragma("unroll") for (int n = 0; n < 2; ++n) _Pragma("unroll") for (int k = 0; k < 2; ++k) \
;         acc[ai][bj][m][n] = __builtin_amdgcn_mfma_f32_16x16x32_bf16(Bt[n][k], At[m][k], acc[ai][bj][m][n], 0, 0, 0); __builtin_amdgcn_s_setprio(0); } while (0)
; #define PG8_WAIT_V(n) asm volatile("s_waitcnt vmcnt(" #n ")" ::: "memory")
; #define PG8_WAIT_L(n) asm volatile("s_waitcnt lgkmcnt(" #n ")" ::: "memory")
; #define PG8_BAR __builtin_amdgcn_s_barrier()
; #define PG8_SCHED __builtin_amdgcn_sched_barrier(0)
; template <class Epi>
; DI void gemm_phase(LAS unsigned char* lds, const Gemm g, const StaticOrder& S, const Epi& E, const int tid) {
;     ...
;             PG8_LDB(B0, 0, 0); PG8_SCHED; PG8_LDA(At, 0, 0); PG8_STAGE(PG8_SA(1, 1), a1 + hstep, voffA);
;             PG8_WAIT_L(8); PG8_BAR; PG8_WAIT_L(0); PG8_MMA(0, 0, At, B0); PG8_BAR; PG8_SCHED;
;             PG8_LDB(B1, 0, 1); PG8_STAGE(PG8_SB(0, 0), b2, voffB);
;     ...
;             PG8_LDA(At, 1, 1); PG8_STAGE(PG8_SA(1, 0), a3, voffA);
;             PG8_BAR; PG8_WAIT_L(0); PG8_MMA(1, 0, At, B0); PG8_BAR; PG8_SCHED;
;             PG8_STAGE(PG8_SB(1, 1), b3 + hstep, voffB);
;             PG8_WAIT_V(6); PG8_BAR; PG8_MMA(1, 1, At, B1); PG8_BAR;
	s_waitcnt lgkmcnt(0)
	s_setprio 1
	v_mfma_f32_16x16x32_bf16 v[60:63], v[138:141], v[162:165], v[60:63]
	v_mfma_f32_16x16x32_bf16 v[68:71], v[154:157], v[162:165], v[68:71]
	v_mfma_f32_16x16x32_bf16 v[48:51], v[138:141], v[170:173], v[48:51]
	v_mfma_f32_16x16x32_bf16 v[52:55], v[154:157], v[170:173], v[52:55]
	v_mfma_f32_16x16x32_bf16 v[40:43], v[138:141], v[178:181], v[40:43]
	v_mfma_f32_16x16x32_bf16 v[44:47], v[154:157], v[178:181], v[44:47]
	v_mfma_f32_16x16x32_bf16 v[32:35], v[138:141], v[186:189], v[32:35]
	v_mfma_f32_16x16x32_bf16 v[36:39], v[154:157], v[186:189], v[36:39]
	v_mfma_f32_16x16x32_bf16 v[60:63], v[150:153], v[166:169], v[60:63]
	v_mfma_f32_16x16x32_bf16 v[68:71], v[158:161], v[166:169], v[68:71]
	v_mfma_f32_16x16x32_bf16 v[48:51], v[150:153], v[174:177], v[48:51]
	v_mfma_f32_16x16x32_bf16 v[52:55], v[158:161], v[174:177], v[52:55]
	v_mfma_f32_16x16x32_bf16 v[40:43], v[150:153], v[182:185], v[40:43]
	v_mfma_f32_16x16x32_bf16 v[44:47], v[158:161], v[182:185], v[44:47]
	v_mfma_f32_16x16x32_bf16 v[32:35], v[150:153], v[190:193], v[32:35]
	v_mfma_f32_16x16x32_bf16 v[36:39], v[158:161], v[190:193], v[36:39]
	s_setprio 0
	s_barrier
	s_add_i32 s18, s18, s4
	s_add_i32 vcc_hi, s60, 2
	s_cmp_eq_u32 vcc_hi, s83
	s_cselect_b32 s100, s16, s81
	s_cselect_b32 s101, s17, s82
	s_add_u32 s100, s100, s84
	s_addc_u32 s101, s101, 0
	s_add_u32 s100, s100, 0x80
	s_addc_u32 s101, s101, 0
	s_mov_b32 m0, s18
	s_nop 0
	global_load_lds_dwordx4 v198, s[100:101]
	s_add_i32 m0, s18, 0x2000
	s_nop 0
	global_load_lds_dwordx4 v128, s[100:101]
	s_add_u32 s20, s20, 0x100
	s_addc_u32 s21, s21, 0
	s_add_u32 s81, s81, 0x100
	s_addc_u32 s82, s82, 0
	s_mov_b32 s18, s83
	s_cmp_ge_u32 s83, s57
	s_waitcnt vmcnt(6)
	s_barrier
	s_setprio 1
	v_mfma_f32_16x16x32_bf16 v[120:123], v[194:197], v[162:165], v[120:123]
	v_mfma_f32_16x16x32_bf16 v[124:127], v[204:207], v[162:165], v[124:127]
	v_mfma_f32_16x16x32_bf16 v[112:115], v[194:197], v[170:173], v[112:115]
	v_mfma_f32_16x16x32_bf16 v[116:119], v[204:207], v[170:173], v[116:119]
	v_mfma_f32_16x16x32_bf16 v[104:107], v[194:197], v[178:181], v[104:107]
	v_mfma_f32_16x16x32_bf16 v[108:111], v[204:207], v[178:181], v[108:111]
	v_mfma_f32_16x16x32_bf16 v[92:95], v[194:197], v[186:189], v[92:95]
	v_mfma_f32_16x16x32_bf16 v[100:103], v[204:207], v[186:189], v[100:103]
	v_mfma_f32_16x16x32_bf16 v[120:123], v[200:203], v[166:169], v[120:123]
	v_mfma_f32_16x16x32_bf16 v[124:127], v[208:211], v[166:169], v[124:127]
	v_mfma_f32_16x16x32_bf16 v[112:115], v[200:203], v[174:177], v[112:115]
	v_mfma_f32_16x16x32_bf16 v[116:119], v[208:211], v[174:177], v[116:119]
	v_mfma_f32_16x16x32_bf16 v[104:107], v[200:203], v[182:185], v[104:107]
	v_mfma_f32_16x16x32_bf16 v[108:111], v[208:211], v[182:185], v[108:111]
	v_mfma_f32_16x16x32_bf16 v[92:95], v[200:203], v[190:193], v[92:95]
	v_mfma_f32_16x16x32_bf16 v[100:103], v[208:211], v[190:193], v[100:103]
	s_setprio 0
	s_barrier
	s_cbranch_scc0 .LBB0_743
	s_branch .Lgemm_epi
.LBB0_743:
	ds_read_b128 v[138:141], v212
	ds_read_b128 v[150:153], v212 offset:1024
	ds_read_b128 v[154:157], v212 offset:2048
	ds_read_b128 v[158:161], v212 offset:3072
	s_add_i32 s83, s18, 2
	s_add_u32 s22, s20, 0x80
	s_addc_u32 s19, s21, 0
	s_cmp_eq_u32 s60, s18
	s_cselect_b32 s18, s8, s22
	s_cselect_b32 s19, s9, s19
	s_cselect_b32 s23, s17, s82
	s_cselect_b32 s22, s16, s81
	s_add_i32 m0, s49, 0xc000
	ds_read_b128 v[162:165], v148
	ds_read_b128 v[166:169], v148 offset:1024
	ds_read_b128 v[170:173], v148 offset:2048
	ds_read_b128 v[174:177], v148 offset:3072
	ds_read_b128 v[178:181], v148 offset:4096
	ds_read_b128 v[182:185], v148 offset:5120
	ds_read_b128 v[186:189], v148 offset:6144
	ds_read_b128 v[190:193], v148 offset:7168
	global_load_lds_dwordx4 v134, s[20:21]
	s_add_i32 m0, s49, 0xe000
	s_nop 0
	global_load_lds_dwordx4 v136, s[20:21]
	s_waitcnt lgkmcnt(8)
	s_barrier
	s_waitcnt lgkmcnt(0)
	s_setprio 1
	v_mfma_f32_16x16x32_bf16 v[24:27], v[138:141], v[162:165], v[24:27]
	v_mfma_f32_16x16x32_bf16 v[28:31], v[154:157], v[162:165], v[28:31]
	v_mfma_f32_16x16x32_bf16 v[16:19], v[138:141], v[170:173], v[16:19]
	v_mfma_f32_16x16x32_bf16 v[20:23], v[154:157], v[170:173], v[20:23]
	v_mfma_f32_16x16x32_bf16 v[8:11], v[138:141], v[178:181], v[8:11]
	v_mfma_f32_16x16x32_bf16 v[12:15], v[154:157], v[178:181], v[12:15]
	v_mfma_f32_16x16x32_bf16 v[0:3], v[138:141], v[186:189], v[0:3]
	v_mfma_f32_16x16x32_bf16 v[4:7], v[154:157], v[186:189], v[4:7]
	v_mfma_f32_16x16x32_bf16 v[24:27], v[150:153], v[166:169], v[24:27]
	v_mfma_f32_16x16x32_bf16 v[28:31], v[158:161], v[166:169], v[28:31]
	v_mfma_f32_16x16x32_bf16 v[16:19], v[150:153], v[174:177], v[16:19]
	v_mfma_f32_16x16x32_bf16 v[20:23], v[158:161], v[174:177], v[20:23]
	v_mfma_f32_16x16x32_bf16 v[8:11], v[150:153], v[182:185], v[8:11]
	v_mfma_f32_16x16x32_bf16 v[12:15], v[158:161], v[182:185], v[12:15]
	v_mfma_f32_16x16x32_bf16 v[0:3], v[150:153], v[190:193], v[0:3]
	v_mfma_f32_16x16x32_bf16 v[4:7], v[158:161], v[190:193], v[4:7]
	s_setprio 0
	s_barrier
	s_add_i32 s89, 0, 0x14000
	s_add_i32 vcc_lo, s26, s4
	s_mov_b32 m0, vcc_lo
	ds_read_b128 v[194:197], v213
	ds_read_b128 v[200:203], v213 offset:1024
	ds_read_b128 v[204:207], v213 offset:2048
	ds_read_b128 v[208:211], v213 offset:3072
	global_load_lds_dwordx4 v198, s[22:23]
	s_add_i32 m0, vcc_lo, 0x2000
	s_nop 0
	global_load_lds_dwordx4 v128, s[22:23]
	s_barrier
; #define PG8_STAGE(bufoff, gbase, voff) do { _Pragma("unroll") for (int _i = 0; _i < 2; ++_i) \
;         __builtin_amdgcn_global_load_lds((const unsigned*)((const char*)(gbase) + (voff)[_i]), (LAS unsigned*)(lds + (bufoff) + ldsw + _i * 8192), 16, 0, 0); } while (0)
; #define PG8_LDA(dst, b, h) do { _Pragma("unroll") for (int m = 0; m < 4; ++m) _Pragma("unroll") for (int k = 0; k < 2; ++k) dst[m][k] = *(const LAS bf16x8*)(lds + PG8_SA(b, h) + aoff + m * 2048 + k * 1024); } while (0)
; #define PG8_LDB(dst, b, h) do { _Pragma("unroll") for (int n = 0; n < 2; ++n) _Pragma("unroll") for (int k = 0; k < 2; ++k) dst[n][k] = *(const LAS bf16x8*)(lds + PG8_SB(b, h) + boff + n * 2048 + k * 1024); } while (0)
; #define PG8_MMA(ai, bj, At, Bt) do { __builtin_amdgcn_s_setprio(1); _Pragma("unroll") for (int m = 0; m < 4; ++m) _Pragma("unroll") for (int n = 0; n < 2; ++n) _Pragma("unroll") for (int k = 0; k < 2; ++k) \
;         acc[ai][bj][m][n] = __builtin_amdgcn_mfma_f32_16x16x32_bf16(Bt[n][k], At[m][k], acc[ai][bj][m][n], 0, 0, 0); __builtin_amdgcn_s_setprio(0); } while (0)
; #define PG8_WAIT_V(n) asm volatile("s_waitcnt vmcnt(" #n ")" ::: "memory")
; #define PG8_WAIT_L(n) asm volatile("s_waitcnt lgkmcnt(" #n ")" ::: "memory")
; #define PG8_BAR __builtin_amdgcn_s_barrier()
; #define PG8_SCHED __builtin_amdgcn_sched_barrier(0)
; template <class Epi>
; DI void gemm_phase(LAS unsigned char* lds, const Gemm g, const StaticOrder& S, const Epi& E, const int tid) {
;     ...
;             PG8_BAR; PG8_WAIT_L(0); PG8_MMA(0, 1, At, B1); PG8_BAR;
;             PG8_LDA(At, 0, 1); PG8_STAGE(PG8_SA(0, 0), a2, voffA);
;             PG8_BAR; PG8_WAIT_L(0); PG8_MMA(1, 0, At, B0); PG8_BAR; PG8_SCHED;
;             PG8_STAGE(PG8_SB(0, 1), b2 + hstep, voffB);
;             PG8_WAIT_V(6); PG8_BAR; PG8_MMA(1, 1, At, B1); PG8_BAR;
;             PG8_LDB(B0, 1, 0); PG8_SCHED; PG8_LDA(At, 1, 0); PG8_STAGE(PG8_SA(0, 1), a2 + hstep, voffA);
;             PG8_WAIT_L(8); PG8_BAR; PG8_WAIT_L(0); PG8_MMA(0, 0, At, B0); PG8_BAR; PG8_SCHED;
;             PG8_LDB(B1, 1, 1); PG8_STAGE(PG8_SB(1, 0), b3, voffB);
;             PG8_BAR; PG8_WAIT_L(0); PG8_MMA(0, 1, At, B1); PG8_BAR;
	s_waitcnt lgkmcnt(0)
	s_setprio 1
	v_mfma_f32_16x16x32_bf16 v[88:91], v[194:197], v[162:165], v[88:91]
	v_mfma_f32_16x16x32_bf16 v[96:99], v[204:207], v[162:165], v[96:99]
	v_mfma_f32_16x16x32_bf16 v[80:83], v[194:197], v[170:173], v[80:83]
	v_mfma_f32_16x16x32_bf16 v[84:87], v[204:207], v[170:173], v[84:87]
	v_mfma_f32_16x16x32_bf16 v[72:75], v[194:197], v[178:181], v[72:75]
	v_mfma_f32_16x16x32_bf16 v[76:79], v[204:207], v[178:181], v[76:79]
	v_mfma_f32_16x16x32_bf16 v[56:59], v[194:197], v[186:189], v[56:59]
	v_mfma_f32_16x16x32_bf16 v[64:67], v[204:207], v[186:189], v[64:67]
	v_mfma_f32_16x16x32_bf16 v[88:91], v[200:203], v[166:169], v[88:91]
	v_mfma_f32_16x16x32_bf16 v[96:99], v[208:211], v[166:169], v[96:99]
	v_mfma_f32_16x16x32_bf16 v[80:83], v[200:203], v[174:177], v[80:83]
	v_mfma_f32_16x16x32_bf16 v[84:87], v[208:211], v[174:177], v[84:87]
	v_mfma_f32_16x16x32_bf16 v[72:75], v[200:203], v[182:185], v[72:75]
	v_mfma_f32_16x16x32_bf16 v[76:79], v[208:211], v[182:185], v[76:79]
	v_mfma_f32_16x16x32_bf16 v[56:59], v[200:203], v[190:193], v[56:59]
	v_mfma_f32_16x16x32_bf16 v[64:67], v[208:211], v[190:193], v[64:67]
	s_setprio 0
	s_barrier
	s_mov_b32 m0, s49
	ds_read_b128 v[162:165], v148 offset:16384
	ds_read_b128 v[166:169], v148 offset:17408
	ds_read_b128 v[170:173], v148 offset:18432
	ds_read_b128 v[174:177], v148 offset:19456
	ds_read_b128 v[178:181], v148 offset:20480
	ds_read_b128 v[182:185], v148 offset:21504
	ds_read_b128 v[186:189], v148 offset:22528
	ds_read_b128 v[190:193], v148 offset:23552
	global_load_lds_dwordx4 v132, s[18:19]
	s_mov_b32 m0, s52
	s_nop 0
	global_load_lds_dwordx4 v130, s[18:19]
	s_barrier
	s_waitcnt lgkmcnt(0)
	s_setprio 1
	v_mfma_f32_16x16x32_bf16 v[60:63], v[138:141], v[162:165], v[60:63]
	v_mfma_f32_16x16x32_bf16 v[68:71], v[154:157], v[162:165], v[68:71]
	v_mfma_f32_16x16x32_bf16 v[48:51], v[138:141], v[170:173], v[48:51]
	v_mfma_f32_16x16x32_bf16 v[52:55], v[154:157], v[170:173], v[52:55]
	v_mfma_f32_16x16x32_bf16 v[40:43], v[138:141], v[178:181], v[40:43]
	v_mfma_f32_16x16x32_bf16 v[44:47], v[154:157], v[178:181], v[44:47]
	v_mfma_f32_16x16x32_bf16 v[32:35], v[138:141], v[186:189], v[32:35]
	v_mfma_f32_16x16x32_bf16 v[36:39], v[154:157], v[186:189], v[36:39]
	v_mfma_f32_16x16x32_bf16 v[60:63], v[150:153], v[166:169], v[60:63]
	v_mfma_f32_16x16x32_bf16 v[68:71], v[158:161], v[166:169], v[68:71]
	v_mfma_f32_16x16x32_bf16 v[48:51], v[150:153], v[174:177], v[48:51]
	v_mfma_f32_16x16x32_bf16 v[52:55], v[158:161], v[174:177], v[52:55]
	v_mfma_f32_16x16x32_bf16 v[40:43], v[150:153], v[182:185], v[40:43]
	v_mfma_f32_16x16x32_bf16 v[44:47], v[158:161], v[182:185], v[44:47]
	v_mfma_f32_16x16x32_bf16 v[32:35], v[150:153], v[190:193], v[32:35]
	v_mfma_f32_16x16x32_bf16 v[36:39], v[158:161], v[190:193], v[36:39]
	s_setprio 0
	s_barrier
	s_add_u32 s22, s22, s84
	s_addc_u32 s23, s23, 0
	s_add_i32 s89, s89, s4
	s_mov_b32 m0, s89
	s_nop 0
	global_load_lds_dwordx4 v198, s[22:23]
	s_add_i32 m0, s89, 0x2000
	s_nop 0
	global_load_lds_dwordx4 v128, s[22:23]
	s_add_i32 s22, 0, 0x18000
	s_waitcnt vmcnt(6)
	s_barrier
	s_setprio 1
	v_mfma_f32_16x16x32_bf16 v[120:123], v[194:197], v[162:165], v[120:123]
	v_mfma_f32_16x16x32_bf16 v[124:127], v[204:207], v[162:165], v[124:127]
	v_mfma_f32_16x16x32_bf16 v[112:115], v[194:197], v[170:173], v[112:115]
	v_mfma_f32_16x16x32_bf16 v[116:119], v[204:207], v[170:173], v[116:119]
	v_mfma_f32_16x16x32_bf16 v[104:107], v[194:197], v[178:181], v[104:107]
	v_mfma_f32_16x16x32_bf16 v[108:111], v[204:207], v[178:181], v[108:111]
	v_mfma_f32_16x16x32_bf16 v[92:95], v[194:197], v[186:189], v[92:95]
	v_mfma_f32_16x16x32_bf16 v[100:103], v[204:207], v[186:189], v[100:103]
	v_mfma_f32_16x16x32_bf16 v[120:123], v[200:203], v[166:169], v[120:123]
	v_mfma_f32_16x16x32_bf16 v[124:127], v[208:211], v[166:169], v[124:127]
	v_mfma_f32_16x16x32_bf16 v[112:115], v[200:203], v[174:177], v[112:115]
	v_mfma_f32_16x16x32_bf16 v[116:119], v[208:211], v[174:177], v[116:119]
	v_mfma_f32_16x16x32_bf16 v[104:107], v[200:203], v[182:185], v[104:107]
	v_mfma_f32_16x16x32_bf16 v[108:111], v[208:211], v[182:185], v[108:111]
	v_mfma_f32_16x16x32_bf16 v[92:95], v[200:203], v[190:193], v[92:95]
	v_mfma_f32_16x16x32_bf16 v[100:103], v[208:211], v[190:193], v[100:103]
	s_setprio 0
	s_barrier
	ds_read_b128 v[138:141], v214
	ds_read_b128 v[150:153], v214 offset:1024
	ds_read_b128 v[154:157], v214 offset:2048
	ds_read_b128 v[158:161], v214 offset:3072
	s_add_u32 s18, s18, s84
	s_addc_u32 s19, s19, 0
	s_mov_b32 m0, s53
	ds_read_b128 v[162:165], v148 offset:32768
	ds_read_b128 v[166:169], v148 offset:33792
	ds_read_b128 v[170:173], v148 offset:34816
	ds_read_b128 v[174:177], v148 offset:35840
	ds_read_b128 v[178:181], v148 offset:36864
	ds_read_b128 v[182:185], v148 offset:37888
	ds_read_b128 v[186:189], v148 offset:38912
	ds_read_b128 v[190:193], v148 offset:39936
	global_load_lds_dwordx4 v132, s[18:19]
	s_mov_b32 m0, s54
	s_nop 0
	global_load_lds_dwordx4 v130, s[18:19]
	s_waitcnt lgkmcnt(8)
	s_barrier
	s_waitcnt lgkmcnt(0)
	s_setprio 1
	v_mfma_f32_16x16x32_bf16 v[24:27], v[138:141], v[162:165], v[24:27]
	v_mfma_f32_16x16x32_bf16 v[28:31], v[154:157], v[162:165], v[28:31]
	v_mfma_f32_16x16x32_bf16 v[16:19], v[138:141], v[170:173], v[16:19]
	v_mfma_f32_16x16x32_bf16 v[20:23], v[154:157], v[170:173], v[20:23]
	v_mfma_f32_16x16x32_bf16 v[8:11], v[138:141], v[178:181], v[8:11]
	v_mfma_f32_16x16x32_bf16 v[12:15], v[154:157], v[178:181], v[12:15]
	v_mfma_f32_16x16x32_bf16 v[0:3], v[138:141], v[186:189], v[0:3]
	v_mfma_f32_16x16x32_bf16 v[4:7], v[154:157], v[186:189], v[4:7]
	v_mfma_f32_16x16x32_bf16 v[24:27], v[150:153], v[166:169], v[24:27]
	v_mfma_f32_16x16x32_bf16 v[28:31], v[158:161], v[166:169], v[28:31]
	v_mfma_f32_16x16x32_bf16 v[16:19], v[150:153], v[174:177], v[16:19]
	v_mfma_f32_16x16x32_bf16 v[20:23], v[158:161], v[174:177], v[20:23]
	v_mfma_f32_16x16x32_bf16 v[8:11], v[150:153], v[182:185], v[8:11]
	v_mfma_f32_16x16x32_bf16 v[12:15], v[158:161], v[182:185], v[12:15]
	v_mfma_f32_16x16x32_bf16 v[0:3], v[150:153], v[190:193], v[0:3]
	v_mfma_f32_16x16x32_bf16 v[4:7], v[158:161], v[190:193], v[4:7]
	s_setprio 0
	s_barrier
; #define PG8_STAGE(bufoff, gbase, voff) do { _Pragma("unroll") for (int _i = 0; _i < 2; ++_i) \
;         __builtin_amdgcn_global_load_lds((const unsigned*)((const char*)(gbase) + (voff)[_i]), (LAS unsigned*)(lds + (bufoff) + ldsw + _i * 8192), 16, 0, 0); } while (0)
; #define PG8_LDA(dst, b, h) do { _Pragma("unroll") for (int m = 0; m < 4; ++m) _Pragma("unroll") for (int k = 0; k < 2; ++k) dst[m][k] = *(const LAS bf16x8*)(lds + PG8_SA(b, h) + aoff + m * 2048 + k * 1024); } while (0)
; #define PG8_LDB(dst, b, h) do { _Pragma("unroll") for (int n = 0; n < 2; ++n) _Pragma("unroll") for (int k = 0; k < 2; ++k) dst[n][k] = *(const LAS bf16x8*)(lds + PG8_SB(b, h) + boff + n * 2048 + k * 1024); } while (0)
; #define PG8_MMA(ai, bj, At, Bt) do { __builtin_amdgcn_s_setprio(1); _Pragma("unroll") for (int m = 0; m < 4; ++m) _Pragma("unroll") for (int n = 0; n < 2; ++n) _Pragma("unroll") for (int k = 0; k < 2; ++k) \
;         acc[ai][bj][m][n] = __builtin_amdgcn_mfma_f32_16x16x32_bf16(Bt[n][k], At[m][k], acc[ai][bj][m][n], 0, 0, 0); __builtin_amdgcn_s_setprio(0); } while (0)
; #define PG8_WAIT_V(n) asm volatile("s_waitcnt vmcnt(" #n ")" ::: "memory")
; #define PG8_WAIT_L(n) asm volatile("s_waitcnt lgkmcnt(" #n ")" ::: "memory")
; #define PG8_BAR __builtin_amdgcn_s_barrier()
; #define PG8_SCHED __builtin_amdgcn_sched_barrier(0)
; template <class Epi>
; DI void gemm_phase(LAS unsigned char* lds, const Gemm g, const StaticOrder& S, const Epi& E, const int tid) {
;     ...
;             PG8_LDB(B1, 1, 1); PG8_STAGE(PG8_SB(1, 0), b3, voffB);
;             PG8_BAR; PG8_WAIT_L(0); PG8_MMA(0, 1, At, B1); PG8_BAR;
;             PG8_LDA(At, 1, 1); PG8_STAGE(PG8_SA(1, 0), a3, voffA);
;             PG8_BAR; PG8_WAIT_L(0); PG8_MMA(1, 0, At, B0); PG8_BAR; PG8_SCHED;
;             PG8_STAGE(PG8_SB(1, 1), b3 + hstep, voffB);
;             PG8_WAIT_V(6); PG8_BAR; PG8_MMA(1, 1, At, B1); PG8_BAR;
	s_add_i32 s18, 0, 0x1c000
	s_add_i32 s19, s22, s4
	s_mov_b32 m0, s19
	ds_read_b128 v[194:197], v215
	ds_read_b128 v[200:203], v215 offset:1024
	ds_read_b128 v[204:207], v215 offset:2048
	ds_read_b128 v[208:211], v215 offset:3072
	s_add_i32 vcc_hi, s60, 2
	s_cmp_eq_u32 vcc_hi, s83
	s_cselect_b32 s100, s16, s81
	s_cselect_b32 s101, s17, s82
	s_add_u32 s100, s100, 0x80
	s_addc_u32 s101, s101, 0
	global_load_lds_dwordx4 v198, s[100:101]
	s_add_i32 m0, s19, 0x2000
	s_nop 0
	global_load_lds_dwordx4 v128, s[100:101]
	s_barrier
	s_waitcnt lgkmcnt(0)
	s_setprio 1
	v_mfma_f32_16x16x32_bf16 v[88:91], v[194:197], v[162:165], v[88:91]
	v_mfma_f32_16x16x32_bf16 v[96:99], v[204:207], v[162:165], v[96:99]
	v_mfma_f32_16x16x32_bf16 v[80:83], v[194:197], v[170:173], v[80:83]
	v_mfma_f32_16x16x32_bf16 v[84:87], v[204:207], v[170:173], v[84:87]
	v_mfma_f32_16x16x32_bf16 v[72:75], v[194:197], v[178:181], v[72:75]
	v_mfma_f32_16x16x32_bf16 v[76:79], v[204:207], v[178:181], v[76:79]
	v_mfma_f32_16x16x32_bf16 v[56:59], v[194:197], v[186:189], v[56:59]
	v_mfma_f32_16x16x32_bf16 v[64:67], v[204:207], v[186:189], v[64:67]
	v_mfma_f32_16x16x32_bf16 v[88:91], v[200:203], v[166:169], v[88:91]
	v_mfma_f32_16x16x32_bf16 v[96:99], v[208:211], v[166:169], v[96:99]
	v_mfma_f32_16x16x32_bf16 v[80:83], v[200:203], v[174:177], v[80:83]
	v_mfma_f32_16x16x32_bf16 v[84:87], v[208:211], v[174:177], v[84:87]
	v_mfma_f32_16x16x32_bf16 v[72:75], v[200:203], v[182:185], v[72:75]
	v_mfma_f32_16x16x32_bf16 v[76:79], v[208:211], v[182:185], v[76:79]
	v_mfma_f32_16x16x32_bf16 v[56:59], v[200:203], v[190:193], v[56:59]
	v_mfma_f32_16x16x32_bf16 v[64:67], v[208:211], v[190:193], v[64:67]
	s_setprio 0
	s_barrier
	s_mov_b32 m0, s55
	ds_read_b128 v[162:165], v148 offset:49152
	ds_read_b128 v[166:169], v148 offset:50176
	ds_read_b128 v[170:173], v148 offset:51200
	ds_read_b128 v[174:177], v148 offset:52224
	ds_read_b128 v[178:181], v148 offset:53248
	ds_read_b128 v[182:185], v148 offset:54272
	ds_read_b128 v[186:189], v148 offset:55296
	ds_read_b128 v[190:193], v148 offset:56320
	s_add_u32 s100, s20, 0x80
	s_addc_u32 s101, s21, 0
	s_add_i32 vcc_hi, s60, 2
	s_cmp_eq_u32 vcc_hi, s83
	s_cselect_b32 s100, s8, s100
	s_cselect_b32 s101, s9, s101
	s_add_u32 s100, s100, 0x80
	s_addc_u32 s101, s101, 0
	global_load_lds_dwordx4 v132, s[100:101]
	s_mov_b32 m0, s56
	s_nop 0
	global_load_lds_dwordx4 v130, s[100:101]
	s_barrier
	s_waitcnt lgkmcnt(0)
	s_setprio 1
	v_mfma_f32_16x16x32_bf16 v[60:63], v[138:141], v[162:165], v[60:63]
	v_mfma_f32_16x16x32_bf16 v[68:71], v[154:157], v[162:165], v[68:71]
	v_mfma_f32_16x16x32_bf16 v[48:51], v[138:141], v[170:173], v[48:51]
	v_mfma_f32_16x16x32_bf16 v[52:55], v[154:157], v[170:173], v[52:55]
	v_mfma_f32_16x16x32_bf16 v[40:43], v[138:141], v[178:181], v[40:43]
	v_mfma_f32_16x16x32_bf16 v[44:47], v[154:157], v[178:181], v[44:47]
	v_mfma_f32_16x16x32_bf16 v[32:35], v[138:141], v[186:189], v[32:35]
	v_mfma_f32_16x16x32_bf16 v[36:39], v[154:157], v[186:189], v[36:39]
	v_mfma_f32_16x16x32_bf16 v[60:63], v[150:153], v[166:169], v[60:63]
	v_mfma_f32_16x16x32_bf16 v[68:71], v[158:161], v[166:169], v[68:71]
	v_mfma_f32_16x16x32_bf16 v[48:51], v[150:153], v[174:177], v[48:51]
	v_mfma_f32_16x16x32_bf16 v[52:55], v[158:161], v[174:177], v[52:55]
	v_mfma_f32_16x16x32_bf16 v[40:43], v[150:153], v[182:185], v[40:43]
	v_mfma_f32_16x16x32_bf16 v[44:47], v[158:161], v[182:185], v[44:47]
	v_mfma_f32_16x16x32_bf16 v[32:35], v[150:153], v[190:193], v[32:35]
	v_mfma_f32_16x16x32_bf16 v[36:39], v[158:161], v[190:193], v[36:39]
	s_setprio 0
	s_barrier
	s_add_i32 s18, s18, s4
	s_add_i32 vcc_hi, s60, 2
	s_cmp_eq_u32 vcc_hi, s83
	s_cselect_b32 s100, s16, s81
	s_cselect_b32 s101, s17, s82
	s_add_u32 s100, s100, s84
	s_addc_u32 s101, s101, 0
	s_add_u32 s100, s100, 0x80
	s_addc_u32 s101, s101, 0
	s_mov_b32 m0, s18
	s_nop 0
	global_load_lds_dwordx4 v198, s[100:101]
	s_add_i32 m0, s18, 0x2000
	s_nop 0
	global_load_lds_dwordx4 v128, s[100:101]
	s_add_u32 s20, s20, 0x100
	s_addc_u32 s21, s21, 0
	s_add_u32 s81, s81, 0x100
	s_addc_u32 s82, s82, 0
	s_mov_b32 s18, s83
	s_cmp_ge_u32 s83, s57
	s_waitcnt vmcnt(6)
	s_barrier
	s_setprio 1
	v_mfma_f32_16x16x32_bf16 v[120:123], v[194:197], v[162:165], v[120:123]
	v_mfma_f32_16x16x32_bf16 v[124:127], v[204:207], v[162:165], v[124:127]
	v_mfma_f32_16x16x32_bf16 v[112:115], v[194:197], v[170:173], v[112:115]
	v_mfma_f32_16x16x32_bf16 v[116:119], v[204:207], v[170:173], v[116:119]
	v_mfma_f32_16x16x32_bf16 v[104:107], v[194:197], v[178:181], v[104:107]
	v_mfma_f32_16x16x32_bf16 v[108:111], v[204:207], v[178:181], v[108:111]
	v_mfma_f32_16x16x32_bf16 v[92:95], v[194:197], v[186:189], v[92:95]
	v_mfma_f32_16x16x32_bf16 v[100:103], v[204:207], v[186:189], v[100:103]
	v_mfma_f32_16x16x32_bf16 v[120:123], v[200:203], v[166:169], v[120:123]
	v_mfma_f32_16x16x32_bf16 v[124:127], v[208:211], v[166:169], v[124:127]
	v_mfma_f32_16x16x32_bf16 v[112:115], v[200:203], v[174:177], v[112:115]
	v_mfma_f32_16x16x32_bf16 v[116:119], v[208:211], v[174:177], v[116:119]
	v_mfma_f32_16x16x32_bf16 v[104:107], v[200:203], v[182:185], v[104:107]
	v_mfma_f32_16x16x32_bf16 v[108:111], v[208:211], v[182:185], v[108:111]
	v_mfma_f32_16x16x32_bf16 v[92:95], v[200:203], v[190:193], v[92:95]
	v_mfma_f32_16x16x32_bf16 v[100:103], v[208:211], v[190:193], v[100:103]
	s_setprio 0
	s_barrier
	s_cbranch_scc0 .LBB0_743
